# static priority raise (s_setprio 1) for the delayed wave half (waves 4-7) through the diff-attention flash loop; reset at the grid barrier
# speedup vs baseline: 1.0069x; 1.0069x over previous
;     ...
;                 for (int r = 0; r < 16; ++r) { s0[r] = __builtin_amdgcn_exp2f(s0[r] - mnew); s1[r] = __builtin_amdgcn_exp2f(s1[r] - mnew); ps += s0[r] + s1[r]; }
;             } else {
; #pragma unroll
;                 for (int r = 0; r < 16; ++r) { s0[r] = __builtin_amdgcn_exp2f(fmaf(s0[r], C2S, -mnew)); s1[r] = __builtin_amdgcn_exp2f(fmaf(s1[r], C2S, -mnew)); ps += s0[r] + s1[r]; }
;             }
;             lsum = lsum * alpha_l + ps;
;     ...
;         __syncthreads();
.LBB0_623:
	v_add_f32_e32 v187, v64, v80
	v_add_f32_e32 v187, 0, v187
	v_add_f32_e32 v191, v65, v81
	v_add_f32_e32 v187, v191, v187
	v_add_f32_e32 v191, v66, v82
	v_add_f32_e32 v187, v191, v187
	v_add_f32_e32 v191, v67, v83
	v_add_f32_e32 v187, v191, v187
	v_add_f32_e32 v191, v68, v84
	v_add_f32_e32 v187, v191, v187
	v_add_f32_e32 v191, v69, v85
	v_add_f32_e32 v187, v191, v187
	v_add_f32_e32 v191, v70, v86
	v_add_f32_e32 v187, v191, v187
	v_add_f32_e32 v191, v71, v87
	v_add_f32_e32 v187, v191, v187
	v_add_f32_e32 v191, v72, v88
	v_add_f32_e32 v187, v191, v187
	v_add_f32_e32 v191, v73, v89
	v_add_f32_e32 v187, v191, v187
	v_add_f32_e32 v191, v74, v90
	v_add_f32_e32 v187, v191, v187
	v_add_f32_e32 v191, v75, v91
	v_add_f32_e32 v187, v191, v187
	v_add_f32_e32 v191, v76, v92
	v_add_f32_e32 v187, v191, v187
	v_add_f32_e32 v191, v77, v93
	v_add_f32_e32 v187, v191, v187
	v_add_f32_e32 v191, v78, v94
	v_add_f32_e32 v187, v191, v187
	v_add_f32_e32 v191, v79, v95
	v_add_f32_e32 v187, v191, v187
	v_fmac_f32_e32 v187, v190, v188
	s_and_b64 vcc, exec, s[42:43]
	s_waitcnt lgkmcnt(0)
	s_barrier
	v_readfirstlane_b32 s100, v194
	s_bitcmp1_b32 s100, 8
	s_cbranch_scc0 .Lda_stag0
	s_sleep 3

;     ...
;         __syncthreads();
	s_setprio 1

;     ...
;                 for (int r = 0; r < 16; ++r) { s0[r] = __builtin_amdgcn_exp2f(s0[r] - mnew); s1[r] = __builtin_amdgcn_exp2f(s1[r] - mnew); ps += s0[r] + s1[r]; }
;             } else {
; #pragma unroll
;                 for (int r = 0; r < 16; ++r) { s0[r] = __builtin_amdgcn_exp2f(fmaf(s0[r], C2S, -mnew)); s1[r] = __builtin_amdgcn_exp2f(fmaf(s1[r], C2S, -mnew)); ps += s0[r] + s1[r]; }
;             }
;             lsum = lsum * alpha_l + ps;
;     ...
;         __syncthreads();
.LBB0_636:
	v_add_f32_e32 v96, v96, v101
	v_add_f32_e32 v96, 0, v96
	v_add_f32_e32 v97, v97, v105
	v_add_f32_e32 v96, v97, v96
	v_add_f32_e32 v97, v98, v106
	v_add_f32_e32 v96, v97, v96
	v_add_f32_e32 v97, v99, v107
	v_add_f32_e32 v96, v97, v96
	v_add_f32_e32 v97, v100, v112
	v_add_f32_e32 v96, v97, v96
	v_add_f32_e32 v97, v102, v113
	v_add_f32_e32 v96, v97, v96
	v_add_f32_e32 v97, v103, v114
	v_add_f32_e32 v96, v97, v96
	v_add_f32_e32 v97, v104, v115
	v_add_f32_e32 v96, v97, v96
	v_add_f32_e32 v97, v108, v120
	v_add_f32_e32 v96, v97, v96
	v_add_f32_e32 v97, v109, v121
	v_add_f32_e32 v96, v97, v96
	v_add_f32_e32 v97, v110, v122
	v_add_f32_e32 v96, v97, v96
	v_add_f32_e32 v97, v111, v123
	v_add_f32_e32 v96, v97, v96
	v_add_f32_e32 v97, v116, v124
	v_add_f32_e32 v96, v97, v96
	v_add_f32_e32 v97, v117, v125
	v_add_f32_e32 v96, v97, v96
	v_add_f32_e32 v97, v118, v126
	v_add_f32_e32 v96, v97, v96
	v_add_f32_e32 v97, v119, v127
	v_add_f32_e32 v96, v97, v96
	v_fmac_f32_e32 v96, v187, v189
	v_mov_b32_e32 v187, v96
	s_waitcnt lgkmcnt(0)
	s_barrier
	v_readfirstlane_b32 s100, v194
	s_bitcmp1_b32 s100, 8
	s_cbranch_scc0 .Lda_stag1
	s_sleep 3

;     ...
;         __syncthreads();
	s_setprio 1

; __device__ __forceinline__ void xcd_barrier(const XcdBarrier& b) {
;     asm volatile("s_waitcnt vmcnt(0)" ::: "memory");
;     __syncthreads();
; __global__ void __launch_bounds__(512, 2) trunk_fwd(Params p) {
;     ...
;         if (did) for (int rep = 0; rep < REP_SYNC; ++rep) xcd_barrier(xbar);
.LBB0_1129:
	s_and_b64 vcc, exec, s[16:17]
	s_cbranch_vccz .LBB0_18
	s_waitcnt vmcnt(0)
	s_waitcnt vmcnt(0)
	s_setprio 0
	s_barrier

; __device__ __forceinline__ void xcd_barrier(const XcdBarrier& b) {
;     ...
;     if (threadIdx.x == 0) {
;         unsigned* bar = b.bar;
;         __builtin_amdgcn_s_waitcnt(0);
;         unsigned nloc = b.st[0], nx = b.st[1];
;         if (nloc == 0u) { xcd_barrier_complete(bar, b.x, nloc, nx); b.st[0] = nloc; b.st[1] = nx; }
	s_and_saveexec_b64 s[16:17], s[96:97]
	s_cbranch_execz .LBB0_17
	v_readlane_b32 s2, v254, 50
	s_waitcnt vmcnt(0) expcnt(0) lgkmcnt(0)
	s_nop 0
	v_mov_b32_e32 v0, s2
	ds_read_b32 v2, v0
	v_readlane_b32 s2, v254, 51
	s_waitcnt lgkmcnt(0)
	v_cmp_ne_u32_e32 vcc, 0, v2
	v_mov_b32_e32 v0, s2
	ds_read_b32 v0, v0
	s_cbranch_vccnz .LBB0_1146
	s_mov_b32 s4, 1
	s_branch .LBB0_1134
